# branch projections of the 512 sample rows hand-written: tiles on waves 0-1 of every workgroup, gate bytes and next K-step fragments in flight during the MFMAs (compiled code did one load-wait round tr
# speedup vs baseline: 1.0203x; 1.0135x over previous
; __device__ __forceinline__ int otid() { int t = threadIdx.x; asm volatile("" : "+v"(t)); return t; }
; __device__ __forceinline__ void tile32(const bf16_t* __restrict__ A, int lda, const bf16_t* __restrict__ Bt, int ldb, int K, int row0, int col0, int lane, f32x4 (&c)[2][2]) {
;   const int i = lane & 15, kg = lane >> 4;
;   const bf16_t* a0 = A + (size_t)(row0 + i) * lda + kg * 8;
;   const bf16_t* a1 = a0 + (size_t)16 * lda;
;   const bf16_t* b0 = Bt + (size_t)(col0 + i) * ldb + kg * 8;
;   const bf16_t* b1 = b0 + (size_t)16 * ldb;
; #pragma unroll 4
;   for (int k = 0; k < K; k += 32) {
;     const bf16x8 af0 = *(const bf16x8*)(a0 + k), af1 = *(const bf16x8*)(a1 + k), bf0 = *(const bf16x8*)(b0 + k), bf1 = *(const bf16x8*)(b1 + k);
;     c[0][0] = __builtin_amdgcn_mfma_f32_16x16x32_bf16(af0, bf0, c[0][0], 0, 0, 0);
;     c[0][1] = __builtin_amdgcn_mfma_f32_16x16x32_bf16(af0, bf1, c[0][1], 0, 0, 0);
;     c[1][0] = __builtin_amdgcn_mfma_f32_16x16x32_bf16(af1, bf0, c[1][0], 0, 0, 0);
;     c[1][1] = __builtin_amdgcn_mfma_f32_16x16x32_bf16(af1, bf1, c[1][1], 0, 0, 0);
;   }
; }
; __device__ __forceinline__ void sample_proj(unsigned char* ws, int l) {
;   const int tid = otid(), lane = tid & 63, gw = blockIdx.x * 8 + (tid >> 6), nw = gridDim.x * 8;
;   const bf16_t* GA = (const bf16_t*)(ws + W_GA);
;   const bf16_t* GB = (const bf16_t*)(ws + W_GB);
;   bf16_t* MRG = (bf16_t*)(ws + W_MRG);
;   for (int t = gw; t < 16 * 32; t += nw) {
;     const int row0 = MP + (t >> 5) * 32, col0 = (t & 31) * 32;
;     f32x4 ca[2][2], cb[2][2];
; #pragma unroll
;     for (int x = 0; x < 2; ++x)
; #pragma unroll
;       for (int y = 0; y < 2; ++y) { ca[x][y] = (f32x4){0.f, 0.f, 0.f, 0.f}; cb[x][y] = (f32x4){0.f, 0.f, 0.f, 0.f}; }
;     tile32((const bf16_t*)(ws + W_OA), 512, (const bf16_t*)(ws + W_WPA) + (size_t)l * 1024 * 512, 512, 512, row0, col0, lane, ca);
;     tile32((const bf16_t*)(ws + W_U), 512, (const bf16_t*)(ws + W_WPB) + (size_t)l * 1024 * 512, 512, 512, row0, col0, lane, cb);
.LBB0_3517:
	s_or_b64 exec, exec, s[0:1]
	v_readlane_b32 s0, v254, 2
	v_readlane_b32 s1, v254, 3
	s_waitcnt lgkmcnt(0)
	s_barrier
	s_load_dwordx2 s[2:3], s[0:1], 0xb0
	v_mov_b32_e32 v1, v244
	v_readlane_b32 s6, v254, 51
	v_readfirstlane_b32 s7, v244
	s_cmp_lg_u32 s6, 0
	s_cbranch_scc1 .Lsproj_orig
	s_waitcnt lgkmcnt(0)
	s_add_u32 s4, s2, 0x7ac0000
	s_addc_u32 s5, s3, 0
	s_mov_b64 s[0:1], exec
	s_lshr_b32 s7, s7, 6
	s_cmp_ge_u32 s7, 2
	s_cbranch_scc1 .LBB0_3524
	v_readlane_b32 s8, v254, 6
	v_readlane_b32 s9, v255, 22
	v_and_b32_e32 v66, 15, v252
	v_lshrrev_b32_e32 v67, 4, v252
	s_lshl_b32 s8, s8, 1
	s_add_i32 s8, s8, s7
	s_lshr_b32 s10, s8, 5
	s_lshl_b32 s10, s10, 5
	s_add_i32 s10, s10, 0x8000
	s_and_b32 s11, s8, 31
	s_lshl_b32 s11, s11, 5
	s_lshl_b32 s12, s10, 10
	s_lshl_b32 s13, s11, 10
	s_lshl_b32 s14, s9, 20
	s_add_i32 s13, s13, s14
	s_add_i32 s15, s12, s11
	s_add_u32 s20, s2, 0x1c402000
	s_addc_u32 s21, s3, 0
	s_add_u32 s20, s20, s12
	s_addc_u32 s21, s21, 0
	s_add_u32 s22, s20, 0x4000
	s_addc_u32 s23, s21, 0
	s_add_u32 s24, s2, 0x1100000
	s_addc_u32 s25, s3, 0
	s_add_u32 s24, s24, s13
	s_addc_u32 s25, s25, 0
	s_add_u32 s26, s24, 0x4000
	s_addc_u32 s27, s25, 0
	s_add_u32 s28, s2, 0xc822000
	s_addc_u32 s29, s3, 0
	s_add_u32 s28, s28, s12
	s_addc_u32 s29, s29, 0
	s_add_u32 s30, s28, 0x4000
	s_addc_u32 s31, s29, 0
	s_add_u32 s42, s2, 0x1300000
	s_addc_u32 s43, s3, 0
	s_add_u32 s42, s42, s13
	s_addc_u32 s43, s43, 0
	s_add_u32 s44, s42, 0x4000
	s_addc_u32 s45, s43, 0
	s_add_u32 s36, s2, 0x10922000
	s_addc_u32 s37, s3, 0
	s_add_u32 s36, s36, s15
	s_addc_u32 s37, s37, 0
	s_add_u32 s38, s2, 0x14a22000
	s_addc_u32 s39, s3, 0
	s_add_u32 s38, s38, s15
	s_addc_u32 s39, s39, 0
	s_lshl_b32 s15, s15, 1
	s_add_u32 s40, s4, s15
	s_addc_u32 s41, s5, 0
	v_lshlrev_b32_e32 v68, 10, v66
	v_lshl_add_u32 v68, v67, 4, v68
	v_lshl_add_u32 v69, v67, 12, v66
	v_mov_b32_e32 v70, v69
	v_add_u32_e32 v71, 0x400, v69
	v_add_u32_e32 v72, 0x800, v69
	v_add_u32_e32 v73, 0xc00, v69
	v_add_u32_e32 v74, 0x4000, v69
	v_add_u32_e32 v75, 0x4400, v69
	v_add_u32_e32 v76, 0x4800, v69
	v_add_u32_e32 v77, 0x4c00, v69
	v_lshlrev_b32_e32 v78, 1, v70
	v_lshlrev_b32_e32 v79, 1, v71
	v_lshlrev_b32_e32 v80, 1, v72
	v_lshlrev_b32_e32 v81, 1, v73
	v_lshlrev_b32_e32 v82, 1, v74
	v_lshlrev_b32_e32 v83, 1, v75
	v_lshlrev_b32_e32 v84, 1, v76
	v_lshlrev_b32_e32 v85, 1, v77
	global_load_ubyte v34, v70, s[36:37]
	global_load_ubyte v50, v70, s[38:39]
	global_load_ubyte v35, v71, s[36:37]
	global_load_ubyte v51, v71, s[38:39]
	global_load_ubyte v36, v72, s[36:37]
	global_load_ubyte v52, v72, s[38:39]
	global_load_ubyte v37, v73, s[36:37]
	global_load_ubyte v53, v73, s[38:39]
	global_load_ubyte v38, v70, s[36:37] offset:16
	global_load_ubyte v54, v70, s[38:39] offset:16
	global_load_ubyte v39, v71, s[36:37] offset:16
	global_load_ubyte v55, v71, s[38:39] offset:16
	global_load_ubyte v40, v72, s[36:37] offset:16
	global_load_ubyte v56, v72, s[38:39] offset:16
	global_load_ubyte v41, v73, s[36:37] offset:16
	global_load_ubyte v57, v73, s[38:39] offset:16
	global_load_ubyte v42, v74, s[36:37]
	global_load_ubyte v58, v74, s[38:39]
	global_load_ubyte v43, v75, s[36:37]
	global_load_ubyte v59, v75, s[38:39]
	global_load_ubyte v44, v76, s[36:37]
	global_load_ubyte v60, v76, s[38:39]
	global_load_ubyte v45, v77, s[36:37]
	global_load_ubyte v61, v77, s[38:39]
	global_load_ubyte v46, v74, s[36:37] offset:16
	global_load_ubyte v62, v74, s[38:39] offset:16
	global_load_ubyte v47, v75, s[36:37] offset:16
	global_load_ubyte v63, v75, s[38:39] offset:16
	global_load_ubyte v48, v76, s[36:37] offset:16
	global_load_ubyte v64, v76, s[38:39] offset:16
	global_load_ubyte v49, v77, s[36:37] offset:16
	global_load_ubyte v65, v77, s[38:39] offset:16
	v_mov_b32_e32 v0, 0
	v_mov_b32_e32 v1, 0
	v_mov_b32_e32 v2, 0
	v_mov_b32_e32 v3, 0
	v_mov_b32_e32 v4, 0
	v_mov_b32_e32 v5, 0
	v_mov_b32_e32 v6, 0
	v_mov_b32_e32 v7, 0
	v_mov_b32_e32 v8, 0
	v_mov_b32_e32 v9, 0
	v_mov_b32_e32 v10, 0
	v_mov_b32_e32 v11, 0
	v_mov_b32_e32 v12, 0
	v_mov_b32_e32 v13, 0
	v_mov_b32_e32 v14, 0
	v_mov_b32_e32 v15, 0
	v_mov_b32_e32 v18, 0
	v_mov_b32_e32 v19, 0
	v_mov_b32_e32 v20, 0
	v_mov_b32_e32 v21, 0
	v_mov_b32_e32 v22, 0
	v_mov_b32_e32 v23, 0
	v_mov_b32_e32 v24, 0
	v_mov_b32_e32 v25, 0
	v_mov_b32_e32 v26, 0
	v_mov_b32_e32 v27, 0
	v_mov_b32_e32 v28, 0
	v_mov_b32_e32 v29, 0
	v_mov_b32_e32 v30, 0
	v_mov_b32_e32 v31, 0
	v_mov_b32_e32 v32, 0
	v_mov_b32_e32 v33, 0
	global_load_dwordx4 v[90:93], v68, s[20:21]
	global_load_dwordx4 v[94:97], v68, s[24:25]
	global_load_dwordx4 v[98:101], v68, s[26:27]
	global_load_dwordx4 v[102:105], v68, s[22:23]
	global_load_dwordx4 v[106:109], v68, s[20:21] offset:64
	global_load_dwordx4 v[110:113], v68, s[24:25] offset:64
	global_load_dwordx4 v[114:117], v68, s[26:27] offset:64
	global_load_dwordx4 v[118:121], v68, s[22:23] offset:64
	global_load_dwordx4 v[122:125], v68, s[20:21] offset:128
	global_load_dwordx4 v[126:129], v68, s[24:25] offset:128
	global_load_dwordx4 v[130:133], v68, s[26:27] offset:128
	global_load_dwordx4 v[134:137], v68, s[22:23] offset:128
	global_load_dwordx4 v[138:141], v68, s[20:21] offset:192
	global_load_dwordx4 v[142:145], v68, s[24:25] offset:192
	global_load_dwordx4 v[146:149], v68, s[26:27] offset:192
	global_load_dwordx4 v[150:153], v68, s[22:23] offset:192
	global_load_dwordx4 v[154:157], v68, s[20:21] offset:256
	global_load_dwordx4 v[158:161], v68, s[24:25] offset:256
	global_load_dwordx4 v[162:165], v68, s[26:27] offset:256
	global_load_dwordx4 v[166:169], v68, s[22:23] offset:256
	global_load_dwordx4 v[170:173], v68, s[20:21] offset:320
	global_load_dwordx4 v[174:177], v68, s[24:25] offset:320
	global_load_dwordx4 v[178:181], v68, s[26:27] offset:320
	global_load_dwordx4 v[182:185], v68, s[22:23] offset:320
	global_load_dwordx4 v[186:189], v68, s[20:21] offset:384
	global_load_dwordx4 v[190:193], v68, s[24:25] offset:384
	global_load_dwordx4 v[194:197], v68, s[26:27] offset:384
	global_load_dwordx4 v[198:201], v68, s[22:23] offset:384
	global_load_dwordx4 v[202:205], v68, s[20:21] offset:448
	global_load_dwordx4 v[206:209], v68, s[24:25] offset:448
	global_load_dwordx4 v[210:213], v68, s[26:27] offset:448
	global_load_dwordx4 v[214:217], v68, s[22:23] offset:448
	s_waitcnt vmcnt(29)
; __device__ __forceinline__ void tile32(const bf16_t* __restrict__ A, int lda, const bf16_t* __restrict__ Bt, int ldb, int K, int row0, int col0, int lane, f32x4 (&c)[2][2]) {
;   const int i = lane & 15, kg = lane >> 4;
;   const bf16_t* a0 = A + (size_t)(row0 + i) * lda + kg * 8;
;   const bf16_t* a1 = a0 + (size_t)16 * lda;
;   const bf16_t* b0 = Bt + (size_t)(col0 + i) * ldb + kg * 8;
;   const bf16_t* b1 = b0 + (size_t)16 * ldb;
; #pragma unroll 4
;   for (int k = 0; k < K; k += 32) {
;     const bf16x8 af0 = *(const bf16x8*)(a0 + k), af1 = *(const bf16x8*)(a1 + k), bf0 = *(const bf16x8*)(b0 + k), bf1 = *(const bf16x8*)(b1 + k);
;     c[0][0] = __builtin_amdgcn_mfma_f32_16x16x32_bf16(af0, bf0, c[0][0], 0, 0, 0);
;     c[0][1] = __builtin_amdgcn_mfma_f32_16x16x32_bf16(af0, bf1, c[0][1], 0, 0, 0);
;     c[1][0] = __builtin_amdgcn_mfma_f32_16x16x32_bf16(af1, bf0, c[1][0], 0, 0, 0);
;     c[1][1] = __builtin_amdgcn_mfma_f32_16x16x32_bf16(af1, bf1, c[1][1], 0, 0, 0);
;   }
	v_mfma_f32_16x16x32_bf16 v[0:3], v[90:93], v[94:97], v[0:3]
	v_mfma_f32_16x16x32_bf16 v[4:7], v[90:93], v[98:101], v[4:7]
	s_waitcnt vmcnt(28)
	v_mfma_f32_16x16x32_bf16 v[8:11], v[102:105], v[94:97], v[8:11]
	v_mfma_f32_16x16x32_bf16 v[12:15], v[102:105], v[98:101], v[12:15]
	s_waitcnt vmcnt(25)
	v_mfma_f32_16x16x32_bf16 v[0:3], v[106:109], v[110:113], v[0:3]
	v_mfma_f32_16x16x32_bf16 v[4:7], v[106:109], v[114:117], v[4:7]
	s_waitcnt vmcnt(24)
	v_mfma_f32_16x16x32_bf16 v[8:11], v[118:121], v[110:113], v[8:11]
	v_mfma_f32_16x16x32_bf16 v[12:15], v[118:121], v[114:117], v[12:15]
	s_waitcnt vmcnt(21)
	v_mfma_f32_16x16x32_bf16 v[0:3], v[122:125], v[126:129], v[0:3]
	v_mfma_f32_16x16x32_bf16 v[4:7], v[122:125], v[130:133], v[4:7]
	s_waitcnt vmcnt(20)
	v_mfma_f32_16x16x32_bf16 v[8:11], v[134:137], v[126:129], v[8:11]
	v_mfma_f32_16x16x32_bf16 v[12:15], v[134:137], v[130:133], v[12:15]
	s_waitcnt vmcnt(17)
	v_mfma_f32_16x16x32_bf16 v[0:3], v[138:141], v[142:145], v[0:3]
	v_mfma_f32_16x16x32_bf16 v[4:7], v[138:141], v[146:149], v[4:7]
	s_waitcnt vmcnt(16)
	v_mfma_f32_16x16x32_bf16 v[8:11], v[150:153], v[142:145], v[8:11]
	v_mfma_f32_16x16x32_bf16 v[12:15], v[150:153], v[146:149], v[12:15]
	global_load_dwordx4 v[90:93], v68, s[20:21] offset:512
	global_load_dwordx4 v[94:97], v68, s[24:25] offset:512
	global_load_dwordx4 v[98:101], v68, s[26:27] offset:512
	global_load_dwordx4 v[102:105], v68, s[22:23] offset:512
	global_load_dwordx4 v[106:109], v68, s[20:21] offset:576
	global_load_dwordx4 v[110:113], v68, s[24:25] offset:576
	global_load_dwordx4 v[114:117], v68, s[26:27] offset:576
	global_load_dwordx4 v[118:121], v68, s[22:23] offset:576
	global_load_dwordx4 v[122:125], v68, s[20:21] offset:640
	global_load_dwordx4 v[126:129], v68, s[24:25] offset:640
	global_load_dwordx4 v[130:133], v68, s[26:27] offset:640
	global_load_dwordx4 v[134:137], v68, s[22:23] offset:640
	global_load_dwordx4 v[138:141], v68, s[20:21] offset:704
	global_load_dwordx4 v[142:145], v68, s[24:25] offset:704
	global_load_dwordx4 v[146:149], v68, s[26:27] offset:704
	global_load_dwordx4 v[150:153], v68, s[22:23] offset:704
	s_waitcnt vmcnt(29)
	v_mfma_f32_16x16x32_bf16 v[0:3], v[154:157], v[158:161], v[0:3]
	v_mfma_f32_16x16x32_bf16 v[4:7], v[154:157], v[162:165], v[4:7]
	s_waitcnt vmcnt(28)
	v_mfma_f32_16x16x32_bf16 v[8:11], v[166:169], v[158:161], v[8:11]
	v_mfma_f32_16x16x32_bf16 v[12:15], v[166:169], v[162:165], v[12:15]
	s_waitcnt vmcnt(25)
	v_mfma_f32_16x16x32_bf16 v[0:3], v[170:173], v[174:177], v[0:3]
	v_mfma_f32_16x16x32_bf16 v[4:7], v[170:173], v[178:181], v[4:7]
	s_waitcnt vmcnt(24)
	v_mfma_f32_16x16x32_bf16 v[8:11], v[182:185], v[174:177], v[8:11]
	v_mfma_f32_16x16x32_bf16 v[12:15], v[182:185], v[178:181], v[12:15]
	s_waitcnt vmcnt(21)
	v_mfma_f32_16x16x32_bf16 v[0:3], v[186:189], v[190:193], v[0:3]
	v_mfma_f32_16x16x32_bf16 v[4:7], v[186:189], v[194:197], v[4:7]
	s_waitcnt vmcnt(20)
	v_mfma_f32_16x16x32_bf16 v[8:11], v[198:201], v[190:193], v[8:11]
	v_mfma_f32_16x16x32_bf16 v[12:15], v[198:201], v[194:197], v[12:15]
	s_waitcnt vmcnt(17)
	v_mfma_f32_16x16x32_bf16 v[0:3], v[202:205], v[206:209], v[0:3]
	v_mfma_f32_16x16x32_bf16 v[4:7], v[202:205], v[210:213], v[4:7]
	s_waitcnt vmcnt(16)
	v_mfma_f32_16x16x32_bf16 v[8:11], v[214:217], v[206:209], v[8:11]
	v_mfma_f32_16x16x32_bf16 v[12:15], v[214:217], v[210:213], v[12:15]
	global_load_dwordx4 v[154:157], v68, s[20:21] offset:768
	global_load_dwordx4 v[158:161], v68, s[24:25] offset:768
	global_load_dwordx4 v[162:165], v68, s[26:27] offset:768
	global_load_dwordx4 v[166:169], v68, s[22:23] offset:768
	global_load_dwordx4 v[170:173], v68, s[20:21] offset:832
	global_load_dwordx4 v[174:177], v68, s[24:25] offset:832
	global_load_dwordx4 v[178:181], v68, s[26:27] offset:832
	global_load_dwordx4 v[182:185], v68, s[22:23] offset:832
	global_load_dwordx4 v[186:189], v68, s[20:21] offset:896
	global_load_dwordx4 v[190:193], v68, s[24:25] offset:896
	global_load_dwordx4 v[194:197], v68, s[26:27] offset:896
	global_load_dwordx4 v[198:201], v68, s[22:23] offset:896
	global_load_dwordx4 v[202:205], v68, s[20:21] offset:960
	global_load_dwordx4 v[206:209], v68, s[24:25] offset:960
	global_load_dwordx4 v[210:213], v68, s[26:27] offset:960
	global_load_dwordx4 v[214:217], v68, s[22:23] offset:960
	s_waitcnt vmcnt(29)
	v_mfma_f32_16x16x32_bf16 v[0:3], v[90:93], v[94:97], v[0:3]
	v_mfma_f32_16x16x32_bf16 v[4:7], v[90:93], v[98:101], v[4:7]
	s_waitcnt vmcnt(28)
	v_mfma_f32_16x16x32_bf16 v[8:11], v[102:105], v[94:97], v[8:11]
	v_mfma_f32_16x16x32_bf16 v[12:15], v[102:105], v[98:101], v[12:15]
	s_waitcnt vmcnt(25)
	v_mfma_f32_16x16x32_bf16 v[0:3], v[106:109], v[110:113], v[0:3]
	v_mfma_f32_16x16x32_bf16 v[4:7], v[106:109], v[114:117], v[4:7]
	s_waitcnt vmcnt(24)
	v_mfma_f32_16x16x32_bf16 v[8:11], v[118:121], v[110:113], v[8:11]
	v_mfma_f32_16x16x32_bf16 v[12:15], v[118:121], v[114:117], v[12:15]
	s_waitcnt vmcnt(21)
	v_mfma_f32_16x16x32_bf16 v[0:3], v[122:125], v[126:129], v[0:3]
	v_mfma_f32_16x16x32_bf16 v[4:7], v[122:125], v[130:133], v[4:7]
	s_waitcnt vmcnt(20)
	v_mfma_f32_16x16x32_bf16 v[8:11], v[134:137], v[126:129], v[8:11]
	v_mfma_f32_16x16x32_bf16 v[12:15], v[134:137], v[130:133], v[12:15]
	s_waitcnt vmcnt(17)
	v_mfma_f32_16x16x32_bf16 v[0:3], v[138:141], v[142:145], v[0:3]
	v_mfma_f32_16x16x32_bf16 v[4:7], v[138:141], v[146:149], v[4:7]
	s_waitcnt vmcnt(16)
; __device__ __forceinline__ void tile32(const bf16_t* __restrict__ A, int lda, const bf16_t* __restrict__ Bt, int ldb, int K, int row0, int col0, int lane, f32x4 (&c)[2][2]) {
;   const int i = lane & 15, kg = lane >> 4;
;   const bf16_t* a0 = A + (size_t)(row0 + i) * lda + kg * 8;
;   const bf16_t* a1 = a0 + (size_t)16 * lda;
;   const bf16_t* b0 = Bt + (size_t)(col0 + i) * ldb + kg * 8;
;   const bf16_t* b1 = b0 + (size_t)16 * ldb;
; #pragma unroll 4
;   for (int k = 0; k < K; k += 32) {
;     const bf16x8 af0 = *(const bf16x8*)(a0 + k), af1 = *(const bf16x8*)(a1 + k), bf0 = *(const bf16x8*)(b0 + k), bf1 = *(const bf16x8*)(b1 + k);
;     c[0][0] = __builtin_amdgcn_mfma_f32_16x16x32_bf16(af0, bf0, c[0][0], 0, 0, 0);
;     c[0][1] = __builtin_amdgcn_mfma_f32_16x16x32_bf16(af0, bf1, c[0][1], 0, 0, 0);
;     c[1][0] = __builtin_amdgcn_mfma_f32_16x16x32_bf16(af1, bf0, c[1][0], 0, 0, 0);
;     c[1][1] = __builtin_amdgcn_mfma_f32_16x16x32_bf16(af1, bf1, c[1][1], 0, 0, 0);
;   }
	v_mfma_f32_16x16x32_bf16 v[8:11], v[150:153], v[142:145], v[8:11]
	v_mfma_f32_16x16x32_bf16 v[12:15], v[150:153], v[146:149], v[12:15]
	global_load_dwordx4 v[90:93], v68, s[28:29]
	global_load_dwordx4 v[94:97], v68, s[42:43]
	global_load_dwordx4 v[98:101], v68, s[44:45]
	global_load_dwordx4 v[102:105], v68, s[30:31]
	global_load_dwordx4 v[106:109], v68, s[28:29] offset:64
	global_load_dwordx4 v[110:113], v68, s[42:43] offset:64
	global_load_dwordx4 v[114:117], v68, s[44:45] offset:64
	global_load_dwordx4 v[118:121], v68, s[30:31] offset:64
	global_load_dwordx4 v[122:125], v68, s[28:29] offset:128
	global_load_dwordx4 v[126:129], v68, s[42:43] offset:128
	global_load_dwordx4 v[130:133], v68, s[44:45] offset:128
	global_load_dwordx4 v[134:137], v68, s[30:31] offset:128
	global_load_dwordx4 v[138:141], v68, s[28:29] offset:192
	global_load_dwordx4 v[142:145], v68, s[42:43] offset:192
	global_load_dwordx4 v[146:149], v68, s[44:45] offset:192
	global_load_dwordx4 v[150:153], v68, s[30:31] offset:192
	s_waitcnt vmcnt(29)
	v_mfma_f32_16x16x32_bf16 v[0:3], v[154:157], v[158:161], v[0:3]
	v_mfma_f32_16x16x32_bf16 v[4:7], v[154:157], v[162:165], v[4:7]
	s_waitcnt vmcnt(28)
	v_mfma_f32_16x16x32_bf16 v[8:11], v[166:169], v[158:161], v[8:11]
	v_mfma_f32_16x16x32_bf16 v[12:15], v[166:169], v[162:165], v[12:15]
	s_waitcnt vmcnt(25)
	v_mfma_f32_16x16x32_bf16 v[0:3], v[170:173], v[174:177], v[0:3]
	v_mfma_f32_16x16x32_bf16 v[4:7], v[170:173], v[178:181], v[4:7]
	s_waitcnt vmcnt(24)
	v_mfma_f32_16x16x32_bf16 v[8:11], v[182:185], v[174:177], v[8:11]
	v_mfma_f32_16x16x32_bf16 v[12:15], v[182:185], v[178:181], v[12:15]
	s_waitcnt vmcnt(21)
	v_mfma_f32_16x16x32_bf16 v[0:3], v[186:189], v[190:193], v[0:3]
	v_mfma_f32_16x16x32_bf16 v[4:7], v[186:189], v[194:197], v[4:7]
	s_waitcnt vmcnt(20)
	v_mfma_f32_16x16x32_bf16 v[8:11], v[198:201], v[190:193], v[8:11]
	v_mfma_f32_16x16x32_bf16 v[12:15], v[198:201], v[194:197], v[12:15]
	s_waitcnt vmcnt(17)
	v_mfma_f32_16x16x32_bf16 v[0:3], v[202:205], v[206:209], v[0:3]
	v_mfma_f32_16x16x32_bf16 v[4:7], v[202:205], v[210:213], v[4:7]
	s_waitcnt vmcnt(16)
	v_mfma_f32_16x16x32_bf16 v[8:11], v[214:217], v[206:209], v[8:11]
	v_mfma_f32_16x16x32_bf16 v[12:15], v[214:217], v[210:213], v[12:15]
	global_load_dwordx4 v[154:157], v68, s[28:29] offset:256
	global_load_dwordx4 v[158:161], v68, s[42:43] offset:256
	global_load_dwordx4 v[162:165], v68, s[44:45] offset:256
	global_load_dwordx4 v[166:169], v68, s[30:31] offset:256
	global_load_dwordx4 v[170:173], v68, s[28:29] offset:320
	global_load_dwordx4 v[174:177], v68, s[42:43] offset:320
	global_load_dwordx4 v[178:181], v68, s[44:45] offset:320
	global_load_dwordx4 v[182:185], v68, s[30:31] offset:320
	global_load_dwordx4 v[186:189], v68, s[28:29] offset:384
	global_load_dwordx4 v[190:193], v68, s[42:43] offset:384
	global_load_dwordx4 v[194:197], v68, s[44:45] offset:384
	global_load_dwordx4 v[198:201], v68, s[30:31] offset:384
	global_load_dwordx4 v[202:205], v68, s[28:29] offset:448
	global_load_dwordx4 v[206:209], v68, s[42:43] offset:448
	global_load_dwordx4 v[210:213], v68, s[44:45] offset:448
	global_load_dwordx4 v[214:217], v68, s[30:31] offset:448
	s_waitcnt vmcnt(29)
	v_mfma_f32_16x16x32_bf16 v[18:21], v[90:93], v[94:97], v[18:21]
	v_mfma_f32_16x16x32_bf16 v[22:25], v[90:93], v[98:101], v[22:25]
	s_waitcnt vmcnt(28)
	v_mfma_f32_16x16x32_bf16 v[26:29], v[102:105], v[94:97], v[26:29]
	v_mfma_f32_16x16x32_bf16 v[30:33], v[102:105], v[98:101], v[30:33]
	s_waitcnt vmcnt(25)
	v_mfma_f32_16x16x32_bf16 v[18:21], v[106:109], v[110:113], v[18:21]
	v_mfma_f32_16x16x32_bf16 v[22:25], v[106:109], v[114:117], v[22:25]
	s_waitcnt vmcnt(24)
	v_mfma_f32_16x16x32_bf16 v[26:29], v[118:121], v[110:113], v[26:29]
	v_mfma_f32_16x16x32_bf16 v[30:33], v[118:121], v[114:117], v[30:33]
	s_waitcnt vmcnt(21)
	v_mfma_f32_16x16x32_bf16 v[18:21], v[122:125], v[126:129], v[18:21]
	v_mfma_f32_16x16x32_bf16 v[22:25], v[122:125], v[130:133], v[22:25]
	s_waitcnt vmcnt(20)
	v_mfma_f32_16x16x32_bf16 v[26:29], v[134:137], v[126:129], v[26:29]
	v_mfma_f32_16x16x32_bf16 v[30:33], v[134:137], v[130:133], v[30:33]
	s_waitcnt vmcnt(17)
	v_mfma_f32_16x16x32_bf16 v[18:21], v[138:141], v[142:145], v[18:21]
	v_mfma_f32_16x16x32_bf16 v[22:25], v[138:141], v[146:149], v[22:25]
	s_waitcnt vmcnt(16)
	v_mfma_f32_16x16x32_bf16 v[26:29], v[150:153], v[142:145], v[26:29]
	v_mfma_f32_16x16x32_bf16 v[30:33], v[150:153], v[146:149], v[30:33]
	global_load_dwordx4 v[90:93], v68, s[28:29] offset:512
	global_load_dwordx4 v[94:97], v68, s[42:43] offset:512
	global_load_dwordx4 v[98:101], v68, s[44:45] offset:512
	global_load_dwordx4 v[102:105], v68, s[30:31] offset:512
	global_load_dwordx4 v[106:109], v68, s[28:29] offset:576
	global_load_dwordx4 v[110:113], v68, s[42:43] offset:576
	global_load_dwordx4 v[114:117], v68, s[44:45] offset:576
	global_load_dwordx4 v[118:121], v68, s[30:31] offset:576
	global_load_dwordx4 v[122:125], v68, s[28:29] offset:640
	global_load_dwordx4 v[126:129], v68, s[42:43] offset:640
	global_load_dwordx4 v[130:133], v68, s[44:45] offset:640
	global_load_dwordx4 v[134:137], v68, s[30:31] offset:640
	global_load_dwordx4 v[138:141], v68, s[28:29] offset:704
	global_load_dwordx4 v[142:145], v68, s[42:43] offset:704
	global_load_dwordx4 v[146:149], v68, s[44:45] offset:704
	global_load_dwordx4 v[150:153], v68, s[30:31] offset:704
	s_waitcnt vmcnt(29)
	v_mfma_f32_16x16x32_bf16 v[18:21], v[154:157], v[158:161], v[18:21]
	v_mfma_f32_16x16x32_bf16 v[22:25], v[154:157], v[162:165], v[22:25]
	s_waitcnt vmcnt(28)
	v_mfma_f32_16x16x32_bf16 v[26:29], v[166:169], v[158:161], v[26:29]
	v_mfma_f32_16x16x32_bf16 v[30:33], v[166:169], v[162:165], v[30:33]
	s_waitcnt vmcnt(25)
; __device__ __forceinline__ void tile32(const bf16_t* __restrict__ A, int lda, const bf16_t* __restrict__ Bt, int ldb, int K, int row0, int col0, int lane, f32x4 (&c)[2][2]) {
;   const int i = lane & 15, kg = lane >> 4;
;   const bf16_t* a0 = A + (size_t)(row0 + i) * lda + kg * 8;
;   const bf16_t* a1 = a0 + (size_t)16 * lda;
;   const bf16_t* b0 = Bt + (size_t)(col0 + i) * ldb + kg * 8;
;   const bf16_t* b1 = b0 + (size_t)16 * ldb;
; #pragma unroll 4
;   for (int k = 0; k < K; k += 32) {
;     const bf16x8 af0 = *(const bf16x8*)(a0 + k), af1 = *(const bf16x8*)(a1 + k), bf0 = *(const bf16x8*)(b0 + k), bf1 = *(const bf16x8*)(b1 + k);
;     c[0][0] = __builtin_amdgcn_mfma_f32_16x16x32_bf16(af0, bf0, c[0][0], 0, 0, 0);
;     c[0][1] = __builtin_amdgcn_mfma_f32_16x16x32_bf16(af0, bf1, c[0][1], 0, 0, 0);
;     c[1][0] = __builtin_amdgcn_mfma_f32_16x16x32_bf16(af1, bf0, c[1][0], 0, 0, 0);
;     c[1][1] = __builtin_amdgcn_mfma_f32_16x16x32_bf16(af1, bf1, c[1][1], 0, 0, 0);
;   }
	v_mfma_f32_16x16x32_bf16 v[18:21], v[170:173], v[174:177], v[18:21]
	v_mfma_f32_16x16x32_bf16 v[22:25], v[170:173], v[178:181], v[22:25]
	s_waitcnt vmcnt(24)
	v_mfma_f32_16x16x32_bf16 v[26:29], v[182:185], v[174:177], v[26:29]
	v_mfma_f32_16x16x32_bf16 v[30:33], v[182:185], v[178:181], v[30:33]
	s_waitcnt vmcnt(21)
	v_mfma_f32_16x16x32_bf16 v[18:21], v[186:189], v[190:193], v[18:21]
	v_mfma_f32_16x16x32_bf16 v[22:25], v[186:189], v[194:197], v[22:25]
	s_waitcnt vmcnt(20)
	v_mfma_f32_16x16x32_bf16 v[26:29], v[198:201], v[190:193], v[26:29]
	v_mfma_f32_16x16x32_bf16 v[30:33], v[198:201], v[194:197], v[30:33]
	s_waitcnt vmcnt(17)
	v_mfma_f32_16x16x32_bf16 v[18:21], v[202:205], v[206:209], v[18:21]
	v_mfma_f32_16x16x32_bf16 v[22:25], v[202:205], v[210:213], v[22:25]
	s_waitcnt vmcnt(16)
	v_mfma_f32_16x16x32_bf16 v[26:29], v[214:217], v[206:209], v[26:29]
	v_mfma_f32_16x16x32_bf16 v[30:33], v[214:217], v[210:213], v[30:33]
	global_load_dwordx4 v[154:157], v68, s[28:29] offset:768
	global_load_dwordx4 v[158:161], v68, s[42:43] offset:768
	global_load_dwordx4 v[162:165], v68, s[44:45] offset:768
	global_load_dwordx4 v[166:169], v68, s[30:31] offset:768
	global_load_dwordx4 v[170:173], v68, s[28:29] offset:832
	global_load_dwordx4 v[174:177], v68, s[42:43] offset:832
	global_load_dwordx4 v[178:181], v68, s[44:45] offset:832
	global_load_dwordx4 v[182:185], v68, s[30:31] offset:832
	global_load_dwordx4 v[186:189], v68, s[28:29] offset:896
	global_load_dwordx4 v[190:193], v68, s[42:43] offset:896
	global_load_dwordx4 v[194:197], v68, s[44:45] offset:896
	global_load_dwordx4 v[198:201], v68, s[30:31] offset:896
	global_load_dwordx4 v[202:205], v68, s[28:29] offset:960
	global_load_dwordx4 v[206:209], v68, s[42:43] offset:960
	global_load_dwordx4 v[210:213], v68, s[44:45] offset:960
	global_load_dwordx4 v[214:217], v68, s[30:31] offset:960
	s_waitcnt vmcnt(29)
	v_mfma_f32_16x16x32_bf16 v[18:21], v[90:93], v[94:97], v[18:21]
	v_mfma_f32_16x16x32_bf16 v[22:25], v[90:93], v[98:101], v[22:25]
	s_waitcnt vmcnt(28)
	v_mfma_f32_16x16x32_bf16 v[26:29], v[102:105], v[94:97], v[26:29]
	v_mfma_f32_16x16x32_bf16 v[30:33], v[102:105], v[98:101], v[30:33]
	s_waitcnt vmcnt(25)
	v_mfma_f32_16x16x32_bf16 v[18:21], v[106:109], v[110:113], v[18:21]
	v_mfma_f32_16x16x32_bf16 v[22:25], v[106:109], v[114:117], v[22:25]
	s_waitcnt vmcnt(24)
	v_mfma_f32_16x16x32_bf16 v[26:29], v[118:121], v[110:113], v[26:29]
	v_mfma_f32_16x16x32_bf16 v[30:33], v[118:121], v[114:117], v[30:33]
	s_waitcnt vmcnt(21)
	v_mfma_f32_16x16x32_bf16 v[18:21], v[122:125], v[126:129], v[18:21]
	v_mfma_f32_16x16x32_bf16 v[22:25], v[122:125], v[130:133], v[22:25]
	s_waitcnt vmcnt(20)
	v_mfma_f32_16x16x32_bf16 v[26:29], v[134:137], v[126:129], v[26:29]
	v_mfma_f32_16x16x32_bf16 v[30:33], v[134:137], v[130:133], v[30:33]
	s_waitcnt vmcnt(17)
	v_mfma_f32_16x16x32_bf16 v[18:21], v[138:141], v[142:145], v[18:21]
	v_mfma_f32_16x16x32_bf16 v[22:25], v[138:141], v[146:149], v[22:25]
	s_waitcnt vmcnt(16)
	v_mfma_f32_16x16x32_bf16 v[26:29], v[150:153], v[142:145], v[26:29]
	v_mfma_f32_16x16x32_bf16 v[30:33], v[150:153], v[146:149], v[30:33]
	s_waitcnt vmcnt(13)
	v_mfma_f32_16x16x32_bf16 v[18:21], v[154:157], v[158:161], v[18:21]
	v_mfma_f32_16x16x32_bf16 v[22:25], v[154:157], v[162:165], v[22:25]
	s_waitcnt vmcnt(12)
	v_mfma_f32_16x16x32_bf16 v[26:29], v[166:169], v[158:161], v[26:29]
	v_mfma_f32_16x16x32_bf16 v[30:33], v[166:169], v[162:165], v[30:33]
	s_waitcnt vmcnt(9)
	v_mfma_f32_16x16x32_bf16 v[18:21], v[170:173], v[174:177], v[18:21]
	v_mfma_f32_16x16x32_bf16 v[22:25], v[170:173], v[178:181], v[22:25]
	s_waitcnt vmcnt(8)
	v_mfma_f32_16x16x32_bf16 v[26:29], v[182:185], v[174:177], v[26:29]
	v_mfma_f32_16x16x32_bf16 v[30:33], v[182:185], v[178:181], v[30:33]
	s_waitcnt vmcnt(5)
	v_mfma_f32_16x16x32_bf16 v[18:21], v[186:189], v[190:193], v[18:21]
	v_mfma_f32_16x16x32_bf16 v[22:25], v[186:189], v[194:197], v[22:25]
	s_waitcnt vmcnt(4)
	v_mfma_f32_16x16x32_bf16 v[26:29], v[198:201], v[190:193], v[26:29]
	v_mfma_f32_16x16x32_bf16 v[30:33], v[198:201], v[194:197], v[30:33]
	s_waitcnt vmcnt(1)
	v_mfma_f32_16x16x32_bf16 v[18:21], v[202:205], v[206:209], v[18:21]
	v_mfma_f32_16x16x32_bf16 v[22:25], v[202:205], v[210:213], v[22:25]
	s_waitcnt vmcnt(0)
	v_mfma_f32_16x16x32_bf16 v[26:29], v[214:217], v[206:209], v[26:29]
	v_mfma_f32_16x16x32_bf16 v[30:33], v[214:217], v[210:213], v[30:33]
	s_waitcnt vmcnt(0)
; __device__ __forceinline__ void sample_proj(unsigned char* ws, int l) {
;     ...
; #pragma unroll
;     for (int rb = 0; rb < 2; ++rb)
; #pragma unroll
;       for (int cc = 0; cc < 2; ++cc)
; #pragma unroll
;         for (int j = 0; j < 4; ++j) {
;           const size_t o = (size_t)(row0 + 16 * rb + (lane >> 4) * 4 + j) * 1024 + col0 + 16 * cc + (lane & 15);
;           const float m = ((float)((const unsigned char*)GA)[o] * ca[rb][cc][j] + (float)((const unsigned char*)GB)[o] * cb[rb][cc][j]) * (1.f / 255.f);
;           MRG[o] = (bf16_t)(cvt_pk_bf16(m, 0.f) & 0xffffu);
;         }
;   }
	s_nop 7
	s_nop 7
	v_cvt_f32_ubyte0_e32 v34, v34
	v_cvt_f32_ubyte0_e32 v50, v50
	v_mul_f32_e32 v50, v18, v50
	v_fmac_f32_e32 v50, v0, v34
	v_mul_f32_e32 v50, 0x3b808081, v50
	v_cvt_pk_bf16_f32 v50, v50, v17
	global_store_short v78, v50, s[40:41]
	v_cvt_f32_ubyte0_e32 v35, v35
	v_cvt_f32_ubyte0_e32 v51, v51
	v_mul_f32_e32 v51, v19, v51
	v_fmac_f32_e32 v51, v1, v35
	v_mul_f32_e32 v51, 0x3b808081, v51
	v_cvt_pk_bf16_f32 v51, v51, v17
	global_store_short v79, v51, s[40:41]
	v_cvt_f32_ubyte0_e32 v36, v36
	v_cvt_f32_ubyte0_e32 v52, v52
	v_mul_f32_e32 v52, v20, v52
	v_fmac_f32_e32 v52, v2, v36
	v_mul_f32_e32 v52, 0x3b808081, v52
	v_cvt_pk_bf16_f32 v52, v52, v17
	global_store_short v80, v52, s[40:41]
	v_cvt_f32_ubyte0_e32 v37, v37
	v_cvt_f32_ubyte0_e32 v53, v53
	v_mul_f32_e32 v53, v21, v53
	v_fmac_f32_e32 v53, v3, v37
	v_mul_f32_e32 v53, 0x3b808081, v53
	v_cvt_pk_bf16_f32 v53, v53, v17
	global_store_short v81, v53, s[40:41]
	v_cvt_f32_ubyte0_e32 v38, v38
	v_cvt_f32_ubyte0_e32 v54, v54
	v_mul_f32_e32 v54, v22, v54
	v_fmac_f32_e32 v54, v4, v38
	v_mul_f32_e32 v54, 0x3b808081, v54
	v_cvt_pk_bf16_f32 v54, v54, v17
	global_store_short v78, v54, s[40:41] offset:32
	v_cvt_f32_ubyte0_e32 v39, v39
	v_cvt_f32_ubyte0_e32 v55, v55
	v_mul_f32_e32 v55, v23, v55
	v_fmac_f32_e32 v55, v5, v39
	v_mul_f32_e32 v55, 0x3b808081, v55
	v_cvt_pk_bf16_f32 v55, v55, v17
	global_store_short v79, v55, s[40:41] offset:32
	v_cvt_f32_ubyte0_e32 v40, v40
	v_cvt_f32_ubyte0_e32 v56, v56
	v_mul_f32_e32 v56, v24, v56
	v_fmac_f32_e32 v56, v6, v40
	v_mul_f32_e32 v56, 0x3b808081, v56
	v_cvt_pk_bf16_f32 v56, v56, v17
	global_store_short v80, v56, s[40:41] offset:32
	v_cvt_f32_ubyte0_e32 v41, v41
	v_cvt_f32_ubyte0_e32 v57, v57
	v_mul_f32_e32 v57, v25, v57
	v_fmac_f32_e32 v57, v7, v41
	v_mul_f32_e32 v57, 0x3b808081, v57
	v_cvt_pk_bf16_f32 v57, v57, v17
	global_store_short v81, v57, s[40:41] offset:32
	v_cvt_f32_ubyte0_e32 v42, v42
	v_cvt_f32_ubyte0_e32 v58, v58
	v_mul_f32_e32 v58, v26, v58
	v_fmac_f32_e32 v58, v8, v42
	v_mul_f32_e32 v58, 0x3b808081, v58
	v_cvt_pk_bf16_f32 v58, v58, v17
	global_store_short v82, v58, s[40:41]
	v_cvt_f32_ubyte0_e32 v43, v43
	v_cvt_f32_ubyte0_e32 v59, v59
	v_mul_f32_e32 v59, v27, v59
	v_fmac_f32_e32 v59, v9, v43
	v_mul_f32_e32 v59, 0x3b808081, v59
	v_cvt_pk_bf16_f32 v59, v59, v17
	global_store_short v83, v59, s[40:41]
	v_cvt_f32_ubyte0_e32 v44, v44
	v_cvt_f32_ubyte0_e32 v60, v60
	v_mul_f32_e32 v60, v28, v60
	v_fmac_f32_e32 v60, v10, v44
	v_mul_f32_e32 v60, 0x3b808081, v60
	v_cvt_pk_bf16_f32 v60, v60, v17
	global_store_short v84, v60, s[40:41]
	v_cvt_f32_ubyte0_e32 v45, v45
	v_cvt_f32_ubyte0_e32 v61, v61
	v_mul_f32_e32 v61, v29, v61
	v_fmac_f32_e32 v61, v11, v45
	v_mul_f32_e32 v61, 0x3b808081, v61
	v_cvt_pk_bf16_f32 v61, v61, v17
	global_store_short v85, v61, s[40:41]
	v_cvt_f32_ubyte0_e32 v46, v46
	v_cvt_f32_ubyte0_e32 v62, v62
	v_mul_f32_e32 v62, v30, v62
	v_fmac_f32_e32 v62, v12, v46
	v_mul_f32_e32 v62, 0x3b808081, v62
	v_cvt_pk_bf16_f32 v62, v62, v17
	global_store_short v82, v62, s[40:41] offset:32
	v_cvt_f32_ubyte0_e32 v47, v47
	v_cvt_f32_ubyte0_e32 v63, v63
	v_mul_f32_e32 v63, v31, v63
	v_fmac_f32_e32 v63, v13, v47
	v_mul_f32_e32 v63, 0x3b808081, v63
	v_cvt_pk_bf16_f32 v63, v63, v17
	global_store_short v83, v63, s[40:41] offset:32
	v_cvt_f32_ubyte0_e32 v48, v48
	v_cvt_f32_ubyte0_e32 v64, v64
	v_mul_f32_e32 v64, v32, v64
	v_fmac_f32_e32 v64, v14, v48
	v_mul_f32_e32 v64, 0x3b808081, v64
	v_cvt_pk_bf16_f32 v64, v64, v17
	global_store_short v84, v64, s[40:41] offset:32
	v_cvt_f32_ubyte0_e32 v49, v49
	v_cvt_f32_ubyte0_e32 v65, v65
	v_mul_f32_e32 v65, v33, v65
	v_fmac_f32_e32 v65, v15, v49
	v_mul_f32_e32 v65, 0x3b808081, v65
	v_cvt_pk_bf16_f32 v65, v65, v17
	global_store_short v85, v65, s[40:41] offset:32
	s_branch .LBB0_3524
.Lsproj_orig:
	v_readlane_b32 s0, v254, 15
	v_ashrrev_i32_e32 v0, 6, v1
	s_waitcnt lgkmcnt(0)
	s_add_u32 s4, s2, 0x7ac0000
	v_add_u32_e32 v40, s0, v0
	s_movk_i32 s0, 0x200
	s_addc_u32 s5, s3, 0
	v_cmp_gt_i32_e32 vcc, s0, v40
	s_and_saveexec_b64 s[0:1], vcc
	s_cbranch_execz .LBB0_3524
	s_add_u32 s6, s2, 0x10922000
	s_addc_u32 s7, s3, 0
	v_readlane_b32 s10, v255, 20
	v_readlane_b32 s12, v255, 22
	s_add_u32 s8, s2, 0x14a22000
	v_readlane_b32 s11, v255, 21
	v_readlane_b32 s13, v255, 23
	s_mov_b32 s10, s12
	s_addc_u32 s9, s3, 0
	v_and_b32_e32 v41, 15, v1
	v_writelane_b32 v255, s12, 22
	s_lshl_b64 s[10:11], s[10:11], 20
	v_lshrrev_b32_e32 v2, 2, v1
	v_and_b32_e32 v34, 48, v1
	v_writelane_b32 v255, s13, 23
	s_add_u32 s10, s2, s10
	v_lshlrev_b32_e32 v1, 9, v41
	v_readlane_b32 s12, v254, 47
	v_and_b32_e32 v42, 12, v2
	v_mov_b32_e32 v35, v17
	s_addc_u32 s11, s3, s11
	v_lshl_add_u32 v43, v0, 5, s12
	v_or_b32_e32 v44, 0x8000, v41
	s_mov_b64 s[12:13], 0
	v_lshlrev_b32_e32 v45, 1, v1
